# v18 + static s_setprio 1 for waves 4-7 inside the DA ring loop
# baseline (speedup 1.0000x reference)
.Lmy_pp_srcdone:
	s_nop 0
	v_lshl_add_u64 v[242:243], s[28:29], 0, v[242:243]
	v_mov_b32_e32 v245, 0
	v_add_u32_e32 v246, 0x10000, v150
	s_lshr_b32 s28, s25, 2
	s_lshl_b32 s28, s28, 12
	s_lshl_b32 s24, s25, 11
	s_add_i32 s24, s24, 0x10000
	v_add_u32_e32 v247, s28, v246
	s_mov_b32 m0, s24
	s_nop 0
	global_load_lds_dwordx4 v[242:243], off
	global_load_lds_dwordx4 v[242:243], off offset:1024
	v_lshl_add_u64 v[242:243], v[244:245], 0, v[242:243]
	s_add_i32 m0, s24, 0x4000
	s_nop 0
	global_load_lds_dwordx4 v[242:243], off
	global_load_lds_dwordx4 v[242:243], off offset:1024
	v_lshl_add_u64 v[242:243], v[244:245], 0, v[242:243]
	s_add_i32 m0, s24, 0x8000
	s_nop 0
	global_load_lds_dwordx4 v[242:243], off
	global_load_lds_dwordx4 v[242:243], off offset:1024
	v_lshl_add_u64 v[242:243], v[244:245], 0, v[242:243]
	s_add_i32 s24, s24, 0xc000
	s_lshr_b32 s29, s25, 2
	s_mov_b32 s25, 0
	s_cmp_eq_u32 s29, 0
	s_cbranch_scc1 .Lmy_pp_noprio
	s_setprio 1
.Lmy_pp_noprio:
	s_waitcnt vmcnt(4)
	s_barrier

.Lmy_pp_nbe_t:
	s_setprio 0
